# input-projection epilogue: eight row-statistic loads issued together; output-projection epilogue: gain reloads ahead of the stores with vmcnt(2)
# speedup vs baseline: 1.0003x; 1.0003x over previous
; #define ER_LOAD(q, buf) do { _Pragma("unroll") for (int mm = 0; mm < 2; ++mm) { const size_t off_ = (size_t)(row0 + ((q) >> 1) * HALF + (2 * ((q) & 1) + mm) * 16) * ldc + col0; \
;             _Pragma("unroll") for (int bj = 0; bj < 2; ++bj) _Pragma("unroll") for (int n = 0; n < 2; ++n) pre[buf][mm][bj][n] = *(const f32x4*)(base + off_ + bj * HALF + n * 16); } } while (0)
;     __device__ __forceinline__ void operator()(const f32x4 (&acc)[2][2][4][2], const Unit& u, int wr, int wc, int fr, int fq) const {
;     ...
;         ER_LOAD(0, 0);
; #pragma unroll
;         for (int q = 0; q < 4; ++q) {
;             if (q == 0) ER_LOAD(1, 1); else if (q == 1) ER_LOAD(2, 0); else if (q == 2) ER_LOAD(3, 1);
; #pragma unroll
;             for (int mm = 0; mm < 2; ++mm) { const int ai = q >> 1, m = 2 * (q & 1) + mm; const size_t off = (size_t)(row0 + ai * HALF + m * 16) * ldc + col0; float ss = 0.f;
;                 const int rl = wr * 64 + fr + ai * HALF + m * 16, cl0 = col0; const size_t xoff = (size_t)u.pm * ((size_t)ldc * BM) + (size_t)rl * 64;
; #pragma unroll
;                 for (int bj = 0; bj < 2; ++bj)
; #pragma unroll
;                     for (int n = 0; n < 2; ++n) {
;                         const f32x4 o = pre[q & 1][mm][bj][n] + acc[ai][bj][m][n] * scale;
;                         *(f32x4*)(out + off + bj * HALF + n * 16) = o;
;                         if (COPY) { const f32x4 gn = *(const f32x4*)(gain + col0 + bj * HALF + n * 16); u32x2_ w; w.x = pk_bf16(o[0] * gn[0], o[1] * gn[1]); w.y = pk_bf16(o[2] * gn[2], o[3] * gn[3]); *(u32x2_*)(XB + xoff + (size_t)((cl0 + bj * HALF + n * 16) >> 6) * (256 * 64) + ((cl0 + bj * HALF + n * 16) & 63)) = w; ss += (o[0] * o[0] + o[1] * o[1]) + (o[2] * o[2] + o[3] * o[3]); } }
;                 if (COPY) { ss += __shfl_xor(ss, 16); ss += __shfl_xor(ss, 32); ssq[2 * q + mm] = ss; } }
;         }
.LBB0_1106:
	v_mov_b32_e32 v187, v214
	v_mov_b32_e32 v189, v216
	s_lshl_b32 s27, s33, 8
	s_or_b32 s27, s27, s60
	v_or_b32_e32 v130, s27, v236
	v_lshl_add_u32 v220, s36, 8, v196
	v_ashrrev_i32_e32 v131, 31, v130
	v_lshlrev_b64 v[224:225], 2, v[130:131]
	v_ashrrev_i32_e32 v221, 31, v220
	v_lshl_add_u64 v[226:227], s[48:49], 0, v[224:225]
	v_lshlrev_b64 v[228:229], 14, v[220:221]
	v_lshl_add_u64 v[134:135], v[226:227], 0, v[228:229]
	global_load_dwordx4 v[130:133], v[134:135], off
	global_load_dwordx4 v[166:169], v[134:135], off offset:64
	v_lshl_add_u64 v[136:137], s[48:49], 0, v[228:229]
	v_lshl_add_u64 v[160:161], v[136:137], 0, v[224:225]
	v_lshl_add_u64 v[222:223], s[16:17], 0, v[224:225]
	s_ashr_i32 s37, s36, 31
	s_lshl_b64 s[36:37], s[36:37], 21
	s_add_u32 s36, s64, s36
	s_addc_u32 s37, s65, s37
	s_ashr_i32 s40, s27, 6
	s_ashr_i32 s41, s40, 31
	v_or_b32_e32 v136, 48, v220
	v_bitop3_b32 v138, s27, 44, v236 bitop3:0xc8
	v_lshl_add_u64 v[250:251], s[36:37], 0, v[198:199]
	s_lshl_b64 s[38:39], s[40:41], 15
	v_ashrrev_i32_e32 v137, 31, v136
	v_lshlrev_b32_e32 v194, 1, v138
	v_lshl_add_u64 v[218:219], v[250:251], 0, s[38:39]
	v_lshlrev_b64 v[230:231], 14, v[136:137]
	v_lshl_add_u64 v[218:219], v[218:219], 0, v[194:195]
	v_lshl_add_u64 v[252:253], v[226:227], 0, v[230:231]
	s_or_b32 s40, s40, 2
	s_ashr_i32 s41, s40, 31
	s_lshl_b64 s[40:41], s[40:41], 15
	s_waitcnt vmcnt(0)
	v_pk_add_f32 v[92:93], v[92:93], v[132:133]
	v_pk_add_f32 v[90:91], v[90:91], v[130:131]
	global_store_dwordx4 v[160:161], v[90:93], off
	global_load_dwordx4 v[174:177], v[222:223], off
	v_or_b32_e32 v130, 16, v220
	v_or_b32_e32 v132, 32, v220
	v_ashrrev_i32_e32 v131, 31, v130
	v_ashrrev_i32_e32 v133, 31, v132
	v_lshlrev_b64 v[248:249], 14, v[130:131]
	v_lshlrev_b64 v[158:159], 14, v[132:133]
	v_pk_add_f32 v[100:101], v[100:101], v[168:169]
	v_pk_add_f32 v[98:99], v[98:99], v[166:167]
	v_lshl_add_u64 v[130:131], v[226:227], 0, v[248:249]
	v_lshl_add_u64 v[132:133], v[226:227], 0, v[158:159]
	global_load_dwordx4 v[178:181], v[134:135], off offset:512
	global_load_dwordx4 v[182:185], v[134:135], off offset:576
	global_load_dwordx4 v[232:235], v[130:131], off
	global_load_dwordx4 v[240:243], v[130:131], off offset:64
	global_load_dwordx4 v[244:247], v[130:131], off offset:512
	global_load_dwordx4 v[150:153], v[130:131], off offset:576
	global_load_dwordx4 v[142:145], v[132:133], off
	global_load_dwordx4 v[138:141], v[132:133], off offset:64
	global_load_dwordx4 v[170:173], v[132:133], off offset:512
	global_load_dwordx4 v[162:165], v[132:133], off offset:576
	global_load_dwordx4 v[154:157], v[252:253], off
	global_load_dwordx4 v[146:149], v[252:253], off offset:64
	global_load_dwordx4 v[134:137], v[252:253], off offset:512
	s_nop 0
	global_load_dwordx4 v[130:133], v[252:253], off offset:576
	v_lshl_add_u64 v[158:159], s[48:49], 0, v[158:159]
	s_waitcnt vmcnt(13)
	v_pk_add_f32 v[108:109], v[108:109], v[180:181]
	v_pk_add_f32 v[106:107], v[106:107], v[178:179]
	v_pk_mul_f32 v[166:167], v[92:93], v[176:177]
	v_pk_mul_f32 v[168:169], v[90:91], v[174:175]
	v_lshl_add_u64 v[174:175], v[250:251], 0, s[40:41]
	v_cvt_pk_bf16_f32 v168, v168, v169
	v_cvt_pk_bf16_f32 v169, v166, v167
	global_store_dwordx2 v[218:219], v[168:169], off
	global_store_dwordx4 v[160:161], v[98:101], off offset:64
	global_load_dwordx4 v[166:169], v[222:223], off offset:64
	v_lshl_add_u64 v[174:175], v[174:175], 0, v[194:195]
	s_waitcnt vmcnt(15)
	v_pk_add_f32 v[116:117], v[116:117], v[184:185]
	v_pk_add_f32 v[114:115], v[114:115], v[182:183]
	s_waitcnt vmcnt(14)
	v_pk_add_f32 v[124:125], v[124:125], v[234:235]
	v_pk_add_f32 v[122:123], v[122:123], v[232:233]
	s_waitcnt vmcnt(13)
	v_pk_add_f32 v[128:129], v[128:129], v[242:243]
	v_pk_add_f32 v[126:127], v[126:127], v[240:241]
	s_waitcnt vmcnt(12)
	v_pk_add_f32 v[120:121], v[120:121], v[246:247]
	v_pk_add_f32 v[118:119], v[118:119], v[244:245]
	s_waitcnt vmcnt(11)
	v_pk_add_f32 v[112:113], v[112:113], v[152:153]
	v_pk_add_f32 v[110:111], v[110:111], v[150:151]
	s_waitcnt vmcnt(10)
	v_pk_add_f32 v[104:105], v[104:105], v[144:145]
	v_pk_add_f32 v[102:103], v[102:103], v[142:143]
	v_lshl_add_u64 v[244:245], s[36:37], 0, v[202:203]
	v_lshl_add_u64 v[234:235], v[228:229], 0, s[18:19]
	v_lshl_add_u64 v[232:233], v[228:229], 0, s[20:21]
	v_lshl_add_u64 v[246:247], v[226:227], 0, v[232:233]
	s_waitcnt vmcnt(9)
	v_pk_add_f32 v[96:97], v[96:97], v[140:141]
	v_pk_add_f32 v[94:95], v[94:95], v[138:139]
	s_waitcnt vmcnt(8)
	v_pk_add_f32 v[88:89], v[88:89], v[172:173]
	v_pk_add_f32 v[86:87], v[86:87], v[170:171]
	s_waitcnt vmcnt(7)
	v_pk_add_f32 v[84:85], v[84:85], v[164:165]
	v_pk_add_f32 v[82:83], v[82:83], v[162:163]
	s_waitcnt vmcnt(6)
	v_pk_add_f32 v[80:81], v[80:81], v[156:157]
	v_pk_add_f32 v[78:79], v[78:79], v[154:155]
	s_waitcnt vmcnt(5)
	v_pk_add_f32 v[76:77], v[76:77], v[148:149]
	v_pk_add_f32 v[74:75], v[74:75], v[146:147]
	s_waitcnt vmcnt(4)
	v_pk_add_f32 v[72:73], v[72:73], v[136:137]
	v_pk_add_f32 v[70:71], v[70:71], v[134:135]
	s_waitcnt vmcnt(3)
	v_pk_add_f32 v[68:69], v[68:69], v[132:133]
	v_pk_add_f32 v[66:67], v[66:67], v[130:131]
	s_waitcnt vmcnt(0)
	v_pk_mul_f32 v[168:169], v[100:101], v[168:169]
	v_pk_mul_f32 v[166:167], v[98:99], v[166:167]
	v_mul_f32_e32 v99, v99, v99
	v_cvt_pk_bf16_f32 v166, v166, v167
	v_cvt_pk_bf16_f32 v167, v168, v169
	global_load_dwordx4 v[214:217], v[222:223], off offset:512
	global_store_dwordx2 v[218:219], v[166:167], off offset:32
	global_store_dwordx4 v[160:161], v[106:109], off offset:512
	v_lshl_add_u64 v[218:219], v[158:159], 0, v[224:225]
	v_mul_f32_e32 v101, v101, v101
	v_fmac_f32_e32 v99, v98, v98
	v_fmac_f32_e32 v101, v100, v100
	s_waitcnt vmcnt(2)
; #define ER_LOAD(q, buf) do { _Pragma("unroll") for (int mm = 0; mm < 2; ++mm) { const size_t off_ = (size_t)(row0 + ((q) >> 1) * HALF + (2 * ((q) & 1) + mm) * 16) * ldc + col0; \
;             _Pragma("unroll") for (int bj = 0; bj < 2; ++bj) _Pragma("unroll") for (int n = 0; n < 2; ++n) pre[buf][mm][bj][n] = *(const f32x4*)(base + off_ + bj * HALF + n * 16); } } while (0)
;     __device__ __forceinline__ void operator()(const f32x4 (&acc)[2][2][4][2], const Unit& u, int wr, int wc, int fr, int fq) const {
;     ...
;         for (int q = 0; q < 4; ++q) {
;             if (q == 0) ER_LOAD(1, 1); else if (q == 1) ER_LOAD(2, 0); else if (q == 2) ER_LOAD(3, 1);
; #pragma unroll
;             for (int mm = 0; mm < 2; ++mm) { const int ai = q >> 1, m = 2 * (q & 1) + mm; const size_t off = (size_t)(row0 + ai * HALF + m * 16) * ldc + col0; float ss = 0.f;
;                 const int rl = wr * 64 + fr + ai * HALF + m * 16, cl0 = col0; const size_t xoff = (size_t)u.pm * ((size_t)ldc * BM) + (size_t)rl * 64;
; #pragma unroll
;                 for (int bj = 0; bj < 2; ++bj)
; #pragma unroll
;                     for (int n = 0; n < 2; ++n) {
;                         const f32x4 o = pre[q & 1][mm][bj][n] + acc[ai][bj][m][n] * scale;
;                         *(f32x4*)(out + off + bj * HALF + n * 16) = o;
;                         if (COPY) { const f32x4 gn = *(const f32x4*)(gain + col0 + bj * HALF + n * 16); u32x2_ w; w.x = pk_bf16(o[0] * gn[0], o[1] * gn[1]); w.y = pk_bf16(o[2] * gn[2], o[3] * gn[3]); *(u32x2_*)(XB + xoff + (size_t)((cl0 + bj * HALF + n * 16) >> 6) * (256 * 64) + ((cl0 + bj * HALF + n * 16) & 63)) = w; ss += (o[0] * o[0] + o[1] * o[1]) + (o[2] * o[2] + o[3] * o[3]); } }
;                 if (COPY) { ss += __shfl_xor(ss, 16); ss += __shfl_xor(ss, 32); ssq[2 * q + mm] = ss; } }
;         }
	v_pk_mul_f32 v[168:169], v[108:109], v[216:217]
	v_pk_mul_f32 v[166:167], v[106:107], v[214:215]
	v_mul_f32_e32 v107, v107, v107
	v_cvt_pk_bf16_f32 v166, v166, v167
	v_cvt_pk_bf16_f32 v167, v168, v169
	global_load_dwordx4 v[214:217], v[222:223], off offset:576
	global_store_dwordx2 v[174:175], v[166:167], off
	global_store_dwordx4 v[160:161], v[114:117], off offset:576
	v_lshl_add_u64 v[160:161], s[48:49], 0, v[248:249]
	v_lshl_add_u64 v[160:161], v[160:161], 0, v[224:225]
	v_mul_f32_e32 v109, v109, v109
	v_fmac_f32_e32 v107, v106, v106
	v_fmac_f32_e32 v109, v108, v108
	s_waitcnt vmcnt(2)
	v_pk_mul_f32 v[168:169], v[116:117], v[216:217]
	v_pk_mul_f32 v[166:167], v[114:115], v[214:215]
	v_mul_f32_e32 v115, v115, v115
	v_cvt_pk_bf16_f32 v166, v166, v167
	v_cvt_pk_bf16_f32 v167, v168, v169
	global_load_dwordx4 v[214:217], v[222:223], off
	global_store_dwordx2 v[174:175], v[166:167], off offset:32
	global_store_dwordx4 v[160:161], v[122:125], off
	v_lshl_add_u64 v[174:175], s[36:37], 0, v[200:201]
	v_lshl_add_u64 v[176:177], v[174:175], 0, s[38:39]
	v_lshl_add_u64 v[176:177], v[176:177], 0, v[194:195]
	v_lshl_add_u64 v[174:175], v[174:175], 0, s[40:41]
	v_lshl_add_u64 v[174:175], v[174:175], 0, v[194:195]
	v_mul_f32_e32 v117, v117, v117
	v_fmac_f32_e32 v115, v114, v114
	v_fmac_f32_e32 v117, v116, v116
	s_waitcnt vmcnt(2)
	v_pk_mul_f32 v[168:169], v[124:125], v[216:217]
	v_pk_mul_f32 v[166:167], v[122:123], v[214:215]
	v_mul_f32_e32 v123, v123, v123
	v_cvt_pk_bf16_f32 v166, v166, v167
	v_cvt_pk_bf16_f32 v167, v168, v169
	global_load_dwordx4 v[214:217], v[222:223], off offset:64
	global_store_dwordx2 v[176:177], v[166:167], off
	global_store_dwordx4 v[160:161], v[126:129], off offset:64
	v_mul_f32_e32 v125, v125, v125
	v_fmac_f32_e32 v123, v122, v122
	v_fmac_f32_e32 v125, v124, v124
	s_waitcnt vmcnt(2)
	v_pk_mul_f32 v[168:169], v[128:129], v[216:217]
	v_pk_mul_f32 v[166:167], v[126:127], v[214:215]
	v_mul_f32_e32 v127, v127, v127
	v_cvt_pk_bf16_f32 v166, v166, v167
	v_cvt_pk_bf16_f32 v167, v168, v169
	global_load_dwordx4 v[214:217], v[222:223], off offset:512
	global_store_dwordx2 v[176:177], v[166:167], off offset:32
	global_store_dwordx4 v[160:161], v[118:121], off offset:512
	v_mul_f32_e32 v129, v129, v129
	v_fmac_f32_e32 v127, v126, v126
	v_fmac_f32_e32 v129, v128, v128
	s_waitcnt vmcnt(2)
	v_pk_mul_f32 v[150:151], v[120:121], v[216:217]
	v_pk_mul_f32 v[152:153], v[118:119], v[214:215]
	v_mul_f32_e32 v119, v119, v119
	v_cvt_pk_bf16_f32 v152, v152, v153
	v_cvt_pk_bf16_f32 v153, v150, v151
	global_load_dwordx4 v[214:217], v[222:223], off offset:576
	global_store_dwordx2 v[174:175], v[152:153], off
	global_store_dwordx4 v[160:161], v[110:113], off offset:576
	v_mul_f32_e32 v121, v121, v121
	v_fmac_f32_e32 v119, v118, v118
	v_fmac_f32_e32 v121, v120, v120
	s_waitcnt vmcnt(2)
	v_pk_mul_f32 v[142:143], v[112:113], v[216:217]
	v_pk_mul_f32 v[144:145], v[110:111], v[214:215]
	v_mul_f32_e32 v111, v111, v111
	v_cvt_pk_bf16_f32 v144, v144, v145
	v_cvt_pk_bf16_f32 v145, v142, v143
	global_store_dwordx2 v[174:175], v[144:145], off offset:32
	global_store_dwordx4 v[218:219], v[102:105], off
	global_load_dwordx4 v[240:243], v[222:223], off
	v_lshl_add_u64 v[144:145], v[244:245], 0, s[38:39]
	v_lshl_add_u64 v[142:143], v[226:227], 0, v[234:235]
	v_lshl_add_u64 v[248:249], v[144:145], 0, v[194:195]
	global_load_dwordx4 v[182:185], v[142:143], off
	global_load_dwordx4 v[178:181], v[142:143], off offset:64
	global_load_dwordx4 v[174:177], v[142:143], off offset:512
	global_load_dwordx4 v[166:169], v[142:143], off offset:576
	global_load_dwordx4 v[158:161], v[246:247], off
	global_load_dwordx4 v[150:153], v[246:247], off offset:64
	s_nop 0
	global_load_dwordx4 v[142:145], v[246:247], off offset:512
	global_load_dwordx4 v[138:141], v[246:247], off offset:576
	v_mul_f32_e32 v113, v113, v113
	v_fmac_f32_e32 v111, v110, v110
	v_fmac_f32_e32 v113, v112, v112
	s_waitcnt vmcnt(7)
	v_pk_add_f32 v[64:65], v[64:65], v[184:185]
	v_pk_add_f32 v[62:63], v[62:63], v[182:183]
	s_waitcnt vmcnt(5)
	v_pk_add_f32 v[56:57], v[56:57], v[176:177]
	v_pk_mul_f32 v[242:243], v[104:105], v[242:243]
	v_pk_mul_f32 v[240:241], v[102:103], v[240:241]
	v_pk_add_f32 v[54:55], v[54:55], v[174:175]
	v_cvt_pk_bf16_f32 v240, v240, v241
	v_cvt_pk_bf16_f32 v241, v242, v243
	global_store_dwordx2 v[248:249], v[240:241], off
	global_store_dwordx4 v[218:219], v[94:97], off offset:64
	global_load_dwordx4 v[240:243], v[222:223], off offset:64
	s_waitcnt vmcnt(7)
	v_pk_add_f32 v[52:53], v[52:53], v[168:169]
	v_pk_add_f32 v[50:51], v[50:51], v[166:167]
	s_waitcnt vmcnt(6)
	v_pk_add_f32 v[48:49], v[48:49], v[160:161]
	v_pk_add_f32 v[46:47], v[46:47], v[158:159]
	s_waitcnt vmcnt(5)
	v_pk_add_f32 v[44:45], v[44:45], v[152:153]
	v_pk_add_f32 v[42:43], v[42:43], v[150:151]
	s_waitcnt vmcnt(4)
	v_pk_add_f32 v[40:41], v[40:41], v[144:145]
	v_pk_add_f32 v[38:39], v[38:39], v[142:143]
	s_waitcnt vmcnt(3)
	v_pk_add_f32 v[36:37], v[36:37], v[140:141]
	v_pk_add_f32 v[34:35], v[34:35], v[138:139]
	v_mul_f32_e32 v103, v103, v103
	v_mul_f32_e32 v105, v105, v105
	v_fmac_f32_e32 v103, v102, v102
	v_fmac_f32_e32 v105, v104, v104
	s_waitcnt vmcnt(0)
	v_pk_mul_f32 v[170:171], v[96:97], v[242:243]
	v_pk_mul_f32 v[172:173], v[94:95], v[240:241]
	v_lshl_add_u64 v[240:241], v[244:245], 0, s[40:41]
	v_cvt_pk_bf16_f32 v172, v172, v173
	v_cvt_pk_bf16_f32 v173, v170, v171
	global_load_dwordx4 v[214:217], v[222:223], off offset:512
	global_store_dwordx2 v[248:249], v[172:173], off offset:32
	global_store_dwordx4 v[218:219], v[86:89], off offset:512
	v_lshl_add_u64 v[240:241], v[240:241], 0, v[194:195]
	s_waitcnt vmcnt(2)
; #define ER_LOAD(q, buf) do { _Pragma("unroll") for (int mm = 0; mm < 2; ++mm) { const size_t off_ = (size_t)(row0 + ((q) >> 1) * HALF + (2 * ((q) & 1) + mm) * 16) * ldc + col0; \
;             _Pragma("unroll") for (int bj = 0; bj < 2; ++bj) _Pragma("unroll") for (int n = 0; n < 2; ++n) pre[buf][mm][bj][n] = *(const f32x4*)(base + off_ + bj * HALF + n * 16); } } while (0)
;     __device__ __forceinline__ void operator()(const f32x4 (&acc)[2][2][4][2], const Unit& u, int wr, int wc, int fr, int fq) const {
;     ...
;         for (int q = 0; q < 4; ++q) {
;             if (q == 0) ER_LOAD(1, 1); else if (q == 1) ER_LOAD(2, 0); else if (q == 2) ER_LOAD(3, 1);
; #pragma unroll
;             for (int mm = 0; mm < 2; ++mm) { const int ai = q >> 1, m = 2 * (q & 1) + mm; const size_t off = (size_t)(row0 + ai * HALF + m * 16) * ldc + col0; float ss = 0.f;
;                 const int rl = wr * 64 + fr + ai * HALF + m * 16, cl0 = col0; const size_t xoff = (size_t)u.pm * ((size_t)ldc * BM) + (size_t)rl * 64;
; #pragma unroll
;                 for (int bj = 0; bj < 2; ++bj)
; #pragma unroll
;                     for (int n = 0; n < 2; ++n) {
;                         const f32x4 o = pre[q & 1][mm][bj][n] + acc[ai][bj][m][n] * scale;
;                         *(f32x4*)(out + off + bj * HALF + n * 16) = o;
;                         if (COPY) { const f32x4 gn = *(const f32x4*)(gain + col0 + bj * HALF + n * 16); u32x2_ w; w.x = pk_bf16(o[0] * gn[0], o[1] * gn[1]); w.y = pk_bf16(o[2] * gn[2], o[3] * gn[3]); *(u32x2_*)(XB + xoff + (size_t)((cl0 + bj * HALF + n * 16) >> 6) * (256 * 64) + ((cl0 + bj * HALF + n * 16) & 63)) = w; ss += (o[0] * o[0] + o[1] * o[1]) + (o[2] * o[2] + o[3] * o[3]); } }
;                 if (COPY) { ss += __shfl_xor(ss, 16); ss += __shfl_xor(ss, 32); ssq[2 * q + mm] = ss; } }
;         }
	v_pk_mul_f32 v[162:163], v[88:89], v[216:217]
	v_pk_mul_f32 v[164:165], v[86:87], v[214:215]
	v_lshl_add_u64 v[170:171], s[48:49], 0, v[230:231]
	v_cvt_pk_bf16_f32 v164, v164, v165
	v_cvt_pk_bf16_f32 v165, v162, v163
	global_load_dwordx4 v[214:217], v[222:223], off offset:576
	global_store_dwordx2 v[240:241], v[164:165], off
	global_store_dwordx4 v[218:219], v[82:85], off offset:576
	v_lshl_add_u64 v[170:171], v[170:171], 0, v[224:225]
	v_lshl_add_u64 v[230:231], v[228:229], 0, s[22:23]
	v_lshl_add_u64 v[228:229], v[228:229], 0, s[24:25]
	v_mul_f32_e32 v87, v87, v87
	v_mul_f32_e32 v89, v89, v89
	v_fmac_f32_e32 v87, v86, v86
	v_fmac_f32_e32 v89, v88, v88
	s_waitcnt vmcnt(2)
	v_pk_mul_f32 v[154:155], v[84:85], v[216:217]
	v_pk_mul_f32 v[156:157], v[82:83], v[214:215]
	v_lshl_add_u64 v[162:163], s[36:37], 0, v[204:205]
	v_cvt_pk_bf16_f32 v156, v156, v157
	v_cvt_pk_bf16_f32 v157, v154, v155
	global_load_dwordx4 v[214:217], v[222:223], off
	global_store_dwordx2 v[240:241], v[156:157], off offset:32
	global_store_dwordx4 v[170:171], v[78:81], off
	v_lshl_add_u64 v[164:165], v[162:163], 0, s[38:39]
	v_lshl_add_u64 v[164:165], v[164:165], 0, v[194:195]
	v_mul_f32_e32 v83, v83, v83
	v_mul_f32_e32 v85, v85, v85
	v_fmac_f32_e32 v83, v82, v82
	v_fmac_f32_e32 v85, v84, v84
	s_waitcnt vmcnt(2)
	v_pk_mul_f32 v[146:147], v[80:81], v[216:217]
	v_pk_mul_f32 v[148:149], v[78:79], v[214:215]
	v_mul_f32_e32 v79, v79, v79
	v_cvt_pk_bf16_f32 v148, v148, v149
	v_cvt_pk_bf16_f32 v149, v146, v147
	global_load_dwordx4 v[214:217], v[222:223], off offset:64
	global_store_dwordx2 v[164:165], v[148:149], off
	global_store_dwordx4 v[170:171], v[74:77], off offset:64
	v_mul_f32_e32 v81, v81, v81
	v_fmac_f32_e32 v79, v78, v78
	v_fmac_f32_e32 v81, v80, v80
	v_add_f32_e32 v79, v79, v81
	v_add_f32_e32 v78, v87, v89
	v_add_f32_e32 v80, v83, v85
	s_waitcnt vmcnt(2)
	v_pk_mul_f32 v[134:135], v[76:77], v[216:217]
	v_pk_mul_f32 v[136:137], v[74:75], v[214:215]
	v_lshl_add_u64 v[146:147], v[162:163], 0, s[40:41]
	v_cvt_pk_bf16_f32 v136, v136, v137
	v_cvt_pk_bf16_f32 v137, v134, v135
	global_load_dwordx4 v[214:217], v[222:223], off offset:512
	global_store_dwordx2 v[164:165], v[136:137], off offset:32
	global_store_dwordx4 v[170:171], v[70:73], off offset:512
	v_lshl_add_u64 v[146:147], v[146:147], 0, v[194:195]
	v_mul_f32_e32 v75, v75, v75
	v_mul_f32_e32 v77, v77, v77
	v_fmac_f32_e32 v75, v74, v74
	v_fmac_f32_e32 v77, v76, v76
	v_add_f32_e32 v74, v103, v105
	v_add_f32_e32 v75, v75, v77
	v_mul_f32_e32 v77, v53, v53
	v_fmac_f32_e32 v77, v52, v52
	s_waitcnt vmcnt(2)
	v_pk_mul_f32 v[130:131], v[72:73], v[216:217]
	v_pk_mul_f32 v[132:133], v[70:71], v[214:215]
	v_lshl_add_u64 v[134:135], s[48:49], 0, v[234:235]
	v_cvt_pk_bf16_f32 v132, v132, v133
	v_cvt_pk_bf16_f32 v133, v130, v131
	global_load_dwordx4 v[214:217], v[222:223], off offset:576
	global_store_dwordx2 v[146:147], v[132:133], off
	global_store_dwordx4 v[170:171], v[66:69], off offset:576
	v_lshl_add_u64 v[218:219], v[134:135], 0, v[224:225]
	v_lshl_add_u64 v[234:235], s[36:37], 0, v[206:207]
	v_lshl_add_u64 v[134:135], v[226:227], 0, v[230:231]
	v_lshl_add_u64 v[226:227], v[226:227], 0, v[228:229]
	v_mul_f32_e32 v71, v71, v71
	v_mul_f32_e32 v73, v73, v73
	v_fmac_f32_e32 v71, v70, v70
	v_fmac_f32_e32 v73, v72, v72
	v_add_f32_e32 v70, v119, v121
	v_add_f32_e32 v71, v71, v73
	v_add_f32_e32 v72, v111, v113
	s_waitcnt vmcnt(2)
	v_pk_mul_f32 v[132:133], v[68:69], v[216:217]
	v_pk_mul_f32 v[130:131], v[66:67], v[214:215]
	v_mul_f32_e32 v67, v67, v67
	v_cvt_pk_bf16_f32 v130, v130, v131
	v_cvt_pk_bf16_f32 v131, v132, v133
	global_store_dwordx2 v[146:147], v[130:131], off offset:32
	global_store_dwordx4 v[218:219], v[62:65], off
	global_load_dwordx4 v[240:243], v[222:223], off
	v_lshl_add_u64 v[130:131], v[234:235], 0, s[38:39]
	v_lshl_add_u64 v[244:245], v[130:131], 0, v[194:195]
	v_pk_add_f32 v[132:133], v[60:61], v[180:181]
	v_pk_add_f32 v[130:131], v[58:59], v[178:179]
	global_load_dwordx4 v[182:185], v[134:135], off
	global_load_dwordx4 v[178:181], v[134:135], off offset:64
	global_load_dwordx4 v[170:173], v[134:135], off offset:512
	global_load_dwordx4 v[162:165], v[134:135], off offset:576
	global_load_dwordx4 v[154:157], v[226:227], off
	global_load_dwordx4 v[146:149], v[226:227], off offset:64
	s_nop 0
	global_load_dwordx4 v[134:137], v[226:227], off offset:512
	global_load_dwordx4 v[58:61], v[226:227], off offset:576
	v_mul_f32_e32 v69, v69, v69
	v_fmac_f32_e32 v67, v66, v66
	v_fmac_f32_e32 v69, v68, v68
	v_add_f32_e32 v66, v123, v125
	v_add_f32_e32 v68, v127, v129
	v_mul_f32_e32 v73, v133, v133
	v_fmac_f32_e32 v73, v132, v132
	v_add_f32_e32 v67, v67, v69
	s_waitcnt vmcnt(7)
	v_pk_add_f32 v[32:33], v[32:33], v[184:185]
	v_pk_add_f32 v[30:31], v[30:31], v[182:183]
	v_pk_mul_f32 v[226:227], v[64:65], v[242:243]
	v_pk_mul_f32 v[240:241], v[62:63], v[240:241]
	s_waitcnt vmcnt(6)
	v_pk_add_f32 v[28:29], v[28:29], v[180:181]
	v_cvt_pk_bf16_f32 v240, v240, v241
	v_cvt_pk_bf16_f32 v241, v226, v227
	global_store_dwordx2 v[244:245], v[240:241], off
	global_store_dwordx4 v[218:219], v[130:133], off offset:64
	global_load_dwordx4 v[240:243], v[222:223], off offset:64
	v_lshl_add_u64 v[226:227], v[234:235], 0, s[40:41]
	v_lshl_add_u64 v[226:227], v[226:227], 0, v[194:195]
	v_pk_add_f32 v[26:27], v[26:27], v[178:179]
	s_waitcnt vmcnt(8)
	v_pk_add_f32 v[24:25], v[24:25], v[172:173]
	v_pk_add_f32 v[22:23], v[22:23], v[170:171]
	s_waitcnt vmcnt(7)
	v_pk_add_f32 v[20:21], v[20:21], v[164:165]
	v_pk_add_f32 v[18:19], v[18:19], v[162:163]
	s_waitcnt vmcnt(6)
	v_pk_add_f32 v[16:17], v[16:17], v[156:157]
	v_pk_add_f32 v[14:15], v[14:15], v[154:155]
	s_waitcnt vmcnt(5)
; #define ER_LOAD(q, buf) do { _Pragma("unroll") for (int mm = 0; mm < 2; ++mm) { const size_t off_ = (size_t)(row0 + ((q) >> 1) * HALF + (2 * ((q) & 1) + mm) * 16) * ldc + col0; \
;             _Pragma("unroll") for (int bj = 0; bj < 2; ++bj) _Pragma("unroll") for (int n = 0; n < 2; ++n) pre[buf][mm][bj][n] = *(const f32x4*)(base + off_ + bj * HALF + n * 16); } } while (0)
;     __device__ __forceinline__ void operator()(const f32x4 (&acc)[2][2][4][2], const Unit& u, int wr, int wc, int fr, int fq) const {
;     ...
;         for (int q = 0; q < 4; ++q) {
;             if (q == 0) ER_LOAD(1, 1); else if (q == 1) ER_LOAD(2, 0); else if (q == 2) ER_LOAD(3, 1);
; #pragma unroll
;             for (int mm = 0; mm < 2; ++mm) { const int ai = q >> 1, m = 2 * (q & 1) + mm; const size_t off = (size_t)(row0 + ai * HALF + m * 16) * ldc + col0; float ss = 0.f;
;                 const int rl = wr * 64 + fr + ai * HALF + m * 16, cl0 = col0; const size_t xoff = (size_t)u.pm * ((size_t)ldc * BM) + (size_t)rl * 64;
; #pragma unroll
;                 for (int bj = 0; bj < 2; ++bj)
; #pragma unroll
;                     for (int n = 0; n < 2; ++n) {
;                         const f32x4 o = pre[q & 1][mm][bj][n] + acc[ai][bj][m][n] * scale;
;                         *(f32x4*)(out + off + bj * HALF + n * 16) = o;
;                         if (COPY) { const f32x4 gn = *(const f32x4*)(gain + col0 + bj * HALF + n * 16); u32x2_ w; w.x = pk_bf16(o[0] * gn[0], o[1] * gn[1]); w.y = pk_bf16(o[2] * gn[2], o[3] * gn[3]); *(u32x2_*)(XB + xoff + (size_t)((cl0 + bj * HALF + n * 16) >> 6) * (256 * 64) + ((cl0 + bj * HALF + n * 16) & 63)) = w; ss += (o[0] * o[0] + o[1] * o[1]) + (o[2] * o[2] + o[3] * o[3]); } }
;                 if (COPY) { ss += __shfl_xor(ss, 16); ss += __shfl_xor(ss, 32); ssq[2 * q + mm] = ss; } }
;         }
	v_pk_add_f32 v[12:13], v[12:13], v[148:149]
	v_pk_add_f32 v[10:11], v[10:11], v[146:147]
	v_and_b32_e32 v147, 64, v239
	v_xor_b32_e32 v146, 16, v239
	v_add_u32_e32 v147, 64, v147
	v_xor_b32_e32 v148, 32, v239
	v_cmp_lt_i32_e32 vcc, v146, v147
	v_mul_f32_e32 v149, v93, v93
	v_fmac_f32_e32 v149, v92, v92
	v_cndmask_b32_e32 v146, v239, v146, vcc
	v_cmp_lt_i32_e32 vcc, v148, v147
	s_waitcnt vmcnt(4)
	v_pk_add_f32 v[92:93], v[8:9], v[136:137]
	v_mul_f32_e32 v63, v63, v63
	v_cndmask_b32_e32 v147, v239, v148, vcc
	v_mul_f32_e32 v148, v91, v91
	v_fmac_f32_e32 v148, v90, v90
	v_pk_add_f32 v[90:91], v[6:7], v[134:135]
	v_mul_f32_e32 v65, v65, v65
	v_fmac_f32_e32 v63, v62, v62
	v_fmac_f32_e32 v65, v64, v64
	v_lshlrev_b32_e32 v146, 2, v146
	v_lshlrev_b32_e32 v147, 2, v147
	s_waitcnt vmcnt(0)
	v_pk_mul_f32 v[174:175], v[132:133], v[242:243]
	v_pk_mul_f32 v[176:177], v[130:131], v[240:241]
	s_nop 0
	v_cvt_pk_bf16_f32 v176, v176, v177
	v_cvt_pk_bf16_f32 v177, v174, v175
	global_load_dwordx4 v[214:217], v[222:223], off offset:512
	global_store_dwordx2 v[244:245], v[176:177], off offset:32
	global_store_dwordx4 v[218:219], v[54:57], off offset:512
	s_waitcnt vmcnt(2)
	v_pk_mul_f32 v[166:167], v[56:57], v[216:217]
	v_pk_mul_f32 v[168:169], v[54:55], v[214:215]
	v_lshl_add_u64 v[174:175], s[48:49], 0, v[232:233]
	v_cvt_pk_bf16_f32 v168, v168, v169
	v_cvt_pk_bf16_f32 v169, v166, v167
	global_load_dwordx4 v[214:217], v[222:223], off offset:576
	global_store_dwordx2 v[226:227], v[168:169], off
	global_store_dwordx4 v[218:219], v[50:53], off offset:576
	v_lshl_add_u64 v[174:175], v[174:175], 0, v[224:225]
	s_waitcnt vmcnt(2)
	v_pk_mul_f32 v[158:159], v[52:53], v[216:217]
	v_pk_mul_f32 v[160:161], v[50:51], v[214:215]
	v_lshl_add_u64 v[166:167], s[36:37], 0, v[208:209]
	v_cvt_pk_bf16_f32 v160, v160, v161
	v_cvt_pk_bf16_f32 v161, v158, v159
	global_load_dwordx4 v[214:217], v[222:223], off
	global_store_dwordx2 v[226:227], v[160:161], off offset:32
	global_store_dwordx4 v[174:175], v[46:49], off
	v_lshl_add_u64 v[168:169], v[166:167], 0, s[38:39]
	v_lshl_add_u64 v[168:169], v[168:169], 0, v[194:195]
	v_pk_add_f32 v[52:53], v[4:5], v[60:61]
	s_waitcnt vmcnt(2)
	v_pk_mul_f32 v[150:151], v[48:49], v[216:217]
	v_pk_mul_f32 v[152:153], v[46:47], v[214:215]
	v_mul_f32_e32 v47, v47, v47
	v_cvt_pk_bf16_f32 v152, v152, v153
	v_cvt_pk_bf16_f32 v153, v150, v151
	global_load_dwordx4 v[214:217], v[222:223], off offset:64
	global_store_dwordx2 v[168:169], v[152:153], off
	global_store_dwordx4 v[174:175], v[42:45], off offset:64
	v_mul_f32_e32 v49, v49, v49
	v_fmac_f32_e32 v47, v46, v46
	v_fmac_f32_e32 v49, v48, v48
	s_waitcnt vmcnt(2)
	v_pk_mul_f32 v[142:143], v[44:45], v[216:217]
	v_pk_mul_f32 v[144:145], v[42:43], v[214:215]
	v_lshl_add_u64 v[150:151], v[166:167], 0, s[40:41]
	v_cvt_pk_bf16_f32 v144, v144, v145
	v_cvt_pk_bf16_f32 v145, v142, v143
	global_load_dwordx4 v[214:217], v[222:223], off offset:512
	global_store_dwordx2 v[168:169], v[144:145], off offset:32
	global_store_dwordx4 v[174:175], v[38:41], off offset:512
	v_lshl_add_u64 v[150:151], v[150:151], 0, v[194:195]
	v_mul_f32_e32 v152, v95, v95
	v_mul_f32_e32 v153, v97, v97
	v_fmac_f32_e32 v152, v94, v94
	v_fmac_f32_e32 v153, v96, v96
	v_add_f32_e32 v76, v152, v153
	v_mul_f32_e32 v43, v43, v43
	v_mul_f32_e32 v45, v45, v45
	v_fmac_f32_e32 v43, v42, v42
	v_fmac_f32_e32 v45, v44, v44
	s_waitcnt vmcnt(2)
	v_pk_mul_f32 v[138:139], v[40:41], v[216:217]
	v_pk_mul_f32 v[140:141], v[38:39], v[214:215]
	v_lshl_add_u64 v[142:143], s[48:49], 0, v[230:231]
	v_cvt_pk_bf16_f32 v140, v140, v141
	v_cvt_pk_bf16_f32 v141, v138, v139
	global_load_dwordx4 v[214:217], v[222:223], off offset:576
	global_store_dwordx2 v[150:151], v[140:141], off
	global_store_dwordx4 v[174:175], v[34:37], off offset:576
	v_lshl_add_u64 v[142:143], v[142:143], 0, v[224:225]
	v_lshl_add_u64 v[144:145], s[36:37], 0, v[210:211]
	v_mul_f32_e32 v39, v39, v39
	v_mul_f32_e32 v41, v41, v41
	v_fmac_f32_e32 v39, v38, v38
	v_fmac_f32_e32 v41, v40, v40
	v_add_f32_e32 v38, v39, v41
	s_waitcnt vmcnt(2)
	v_pk_mul_f32 v[140:141], v[36:37], v[216:217]
	v_pk_mul_f32 v[138:139], v[34:35], v[214:215]
	v_mul_f32_e32 v35, v35, v35
	v_cvt_pk_bf16_f32 v138, v138, v139
	v_cvt_pk_bf16_f32 v139, v140, v141
	global_load_dwordx4 v[214:217], v[222:223], off
	global_store_dwordx2 v[150:151], v[138:139], off offset:32
	global_store_dwordx4 v[142:143], v[30:33], off
	v_lshl_add_u64 v[150:151], v[144:145], 0, s[38:39]
	v_lshl_add_u64 v[150:151], v[150:151], 0, v[194:195]
	v_lshl_add_u64 v[144:145], v[144:145], 0, s[40:41]
	v_lshl_add_u64 v[144:145], v[144:145], 0, v[194:195]
	v_mul_f32_e32 v37, v37, v37
	v_fmac_f32_e32 v35, v34, v34
	v_fmac_f32_e32 v37, v36, v36
	v_add_f32_e32 v34, v47, v49
	v_add_f32_e32 v36, v43, v45
	v_add_f32_e32 v35, v35, v37
	s_waitcnt vmcnt(2)
	v_pk_mul_f32 v[140:141], v[32:33], v[216:217]
	v_pk_mul_f32 v[138:139], v[30:31], v[214:215]
	s_nop 0
	v_cvt_pk_bf16_f32 v138, v138, v139
	v_cvt_pk_bf16_f32 v139, v140, v141
	global_load_dwordx4 v[214:217], v[222:223], off offset:64
	global_store_dwordx2 v[150:151], v[138:139], off
	global_store_dwordx4 v[142:143], v[26:29], off offset:64
	s_waitcnt vmcnt(2)
	v_pk_mul_f32 v[140:141], v[28:29], v[216:217]
	v_pk_mul_f32 v[138:139], v[26:27], v[214:215]
	v_mul_f32_e32 v27, v27, v27
	v_cvt_pk_bf16_f32 v138, v138, v139
	v_cvt_pk_bf16_f32 v139, v140, v141
	global_load_dwordx4 v[214:217], v[222:223], off offset:512
	global_store_dwordx2 v[150:151], v[138:139], off offset:32
	global_store_dwordx4 v[142:143], v[22:25], off offset:512
	v_mul_f32_e32 v29, v29, v29
	v_fmac_f32_e32 v27, v26, v26
	v_fmac_f32_e32 v29, v28, v28
	s_waitcnt vmcnt(2)
;     __device__ __forceinline__ void operator()(const f32x4 (&acc)[2][2][4][2], const Unit& u, int wr, int wc, int fr, int fq) const {
;     ...
;                         const f32x4 o = pre[q & 1][mm][bj][n] + acc[ai][bj][m][n] * scale;
;                         *(f32x4*)(out + off + bj * HALF + n * 16) = o;
;                         if (COPY) { const f32x4 gn = *(const f32x4*)(gain + col0 + bj * HALF + n * 16); u32x2_ w; w.x = pk_bf16(o[0] * gn[0], o[1] * gn[1]); w.y = pk_bf16(o[2] * gn[2], o[3] * gn[3]); *(u32x2_*)(XB + xoff + (size_t)((cl0 + bj * HALF + n * 16) >> 6) * (256 * 64) + ((cl0 + bj * HALF + n * 16) & 63)) = w; ss += (o[0] * o[0] + o[1] * o[1]) + (o[2] * o[2] + o[3] * o[3]); } }
;                 if (COPY) { ss += __shfl_xor(ss, 16); ss += __shfl_xor(ss, 32); ssq[2 * q + mm] = ss; } }
;         }
;     ...
;         if (COPY) { if (fq == 0) {
; #pragma unroll
;             for (int i = 0; i < 8; ++i) atomicAdd(stat + row0 + (i >> 2) * HALF + (i & 3) * 16, ssq[i]); } }
	v_pk_mul_f32 v[140:141], v[24:25], v[216:217]
	v_pk_mul_f32 v[138:139], v[22:23], v[214:215]
	v_mul_f32_e32 v23, v23, v23
	v_cvt_pk_bf16_f32 v138, v138, v139
	v_cvt_pk_bf16_f32 v139, v140, v141
	global_load_dwordx4 v[214:217], v[222:223], off offset:576
	global_store_dwordx2 v[144:145], v[138:139], off
	global_store_dwordx4 v[142:143], v[18:21], off offset:576
	v_lshl_add_u64 v[138:139], s[48:49], 0, v[228:229]
	v_lshl_add_u64 v[138:139], v[138:139], 0, v[224:225]
	v_mul_f32_e32 v25, v25, v25
	v_fmac_f32_e32 v23, v22, v22
	v_fmac_f32_e32 v25, v24, v24
	s_waitcnt vmcnt(2)
	v_pk_mul_f32 v[142:143], v[20:21], v[216:217]
	v_pk_mul_f32 v[140:141], v[18:19], v[214:215]
	v_mul_f32_e32 v19, v19, v19
	v_cvt_pk_bf16_f32 v140, v140, v141
	v_cvt_pk_bf16_f32 v141, v142, v143
	global_load_dwordx4 v[214:217], v[222:223], off
	global_store_dwordx2 v[144:145], v[140:141], off offset:32
	global_store_dwordx4 v[138:139], v[14:17], off
	v_lshl_add_u64 v[144:145], s[36:37], 0, v[212:213]
	v_lshl_add_u64 v[150:151], v[144:145], 0, s[38:39]
	v_lshl_add_u64 v[150:151], v[150:151], 0, v[194:195]
	v_lshl_add_u64 v[144:145], v[144:145], 0, s[40:41]
	v_mul_f32_e32 v21, v21, v21
	v_fmac_f32_e32 v19, v18, v18
	v_fmac_f32_e32 v21, v20, v20
	s_waitcnt vmcnt(2)
	v_pk_mul_f32 v[142:143], v[16:17], v[216:217]
	v_pk_mul_f32 v[140:141], v[14:15], v[214:215]
	v_mul_f32_e32 v15, v15, v15
	v_cvt_pk_bf16_f32 v140, v140, v141
	v_cvt_pk_bf16_f32 v141, v142, v143
	global_load_dwordx4 v[214:217], v[222:223], off offset:64
	global_store_dwordx2 v[150:151], v[140:141], off
	global_store_dwordx4 v[138:139], v[10:13], off offset:64
	v_mul_f32_e32 v17, v17, v17
	v_fmac_f32_e32 v15, v14, v14
	v_fmac_f32_e32 v17, v16, v16
	v_add_f32_e32 v15, v15, v17
	v_add_f32_e32 v14, v19, v21
	s_waitcnt vmcnt(2)
	v_pk_mul_f32 v[6:7], v[12:13], v[216:217]
	v_pk_mul_f32 v[8:9], v[10:11], v[214:215]
	v_mov_b32_e32 v214, v187
	v_mov_b32_e32 v216, v189
	v_mov_b32_e32 v187, v195
	v_mov_b32_e32 v189, v195
	v_mov_b32_e32 v215, v195
	v_mov_b32_e32 v217, v195
	v_mul_f32_e32 v11, v11, v11
	v_cvt_pk_bf16_f32 v8, v8, v9
	v_cvt_pk_bf16_f32 v9, v6, v7
	global_store_dwordx2 v[150:151], v[8:9], off offset:32
	global_store_dwordx4 v[138:139], v[90:93], off offset:512
	global_load_dwordx4 v[94:97], v[222:223], off offset:512
	v_add_f32_e32 v6, v148, v149
	v_add_f32_e32 v7, v99, v101
	v_add_f32_e32 v6, v6, v7
	v_add_f32_e32 v7, v66, v68
	v_add_f32_e32 v66, v74, v76
	v_mul_f32_e32 v76, v51, v51
	v_add_f32_e32 v8, v107, v109
	v_add_f32_e32 v68, v79, v75
	v_fmac_f32_e32 v76, v50, v50
	v_pk_add_f32 v[50:51], v[2:3], v[58:59]
	v_add_f32_e32 v6, v6, v8
	v_add_f32_e32 v7, v7, v70
	v_add_f32_e32 v8, v66, v78
	v_add_f32_e32 v66, v68, v71
	v_lshl_add_u64 v[70:71], v[144:145], 0, v[194:195]
	v_mul_f32_e32 v74, v55, v55
	v_mul_f32_e32 v75, v57, v57
	v_fmac_f32_e32 v74, v54, v54
	v_fmac_f32_e32 v75, v56, v56
	v_add_f32_e32 v7, v7, v72
	v_mul_f32_e32 v72, v131, v131
	v_fmac_f32_e32 v72, v130, v130
	v_mul_f32_e32 v13, v13, v13
	v_fmac_f32_e32 v11, v10, v10
	v_fmac_f32_e32 v13, v12, v12
	v_add_f32_e32 v10, v27, v29
	v_add_f32_e32 v11, v11, v13
	v_add_f32_e32 v12, v23, v25
	v_add_f32_e32 v9, v115, v117
	v_add_f32_e32 v6, v6, v9
	v_add_f32_e32 v8, v8, v80
	v_add_f32_e32 v66, v66, v67
	ds_bpermute_b32 v9, v146, v6
	ds_bpermute_b32 v67, v146, v7
	ds_bpermute_b32 v68, v146, v8
	ds_bpermute_b32 v69, v146, v66
	s_waitcnt lgkmcnt(3)
	v_add_f32_e32 v6, v6, v9
	s_waitcnt lgkmcnt(2)
	v_add_f32_e32 v7, v7, v67
	s_waitcnt lgkmcnt(1)
	v_add_f32_e32 v9, v8, v68
	s_waitcnt lgkmcnt(0)
	v_add_f32_e32 v67, v66, v69
	ds_bpermute_b32 v8, v147, v6
	ds_bpermute_b32 v66, v147, v7
	ds_bpermute_b32 v68, v147, v9
	ds_bpermute_b32 v69, v147, v67
	s_waitcnt vmcnt(0)
	v_pk_mul_f32 v[2:3], v[92:93], v[96:97]
	v_pk_mul_f32 v[4:5], v[90:91], v[94:95]
	s_nop 0
	v_cvt_pk_bf16_f32 v4, v4, v5
	v_cvt_pk_bf16_f32 v5, v2, v3
	global_store_dwordx2 v[70:71], v[4:5], off
	global_store_dwordx4 v[138:139], v[50:53], off offset:576
	global_load_dwordx4 v[54:57], v[222:223], off offset:576
	v_add_f32_e32 v2, v63, v65
	v_add_f32_e32 v3, v72, v73
	v_add_f32_e32 v4, v74, v75
	v_add_f32_e32 v2, v2, v3
	v_add_f32_e32 v5, v76, v77
	v_add_f32_e32 v2, v2, v4
	v_add_f32_e32 v2, v2, v5
	ds_bpermute_b32 v3, v146, v2
	v_add_f32_e32 v4, v34, v36
	v_add_f32_e32 v4, v4, v38
	v_mul_f32_e32 v34, v93, v93
	v_add_f32_e32 v4, v4, v35
	s_waitcnt lgkmcnt(0)
	v_add_f32_e32 v2, v2, v3
	v_mul_f32_e32 v3, v31, v31
	v_mul_f32_e32 v31, v33, v33
	v_mul_f32_e32 v33, v91, v91
	v_fmac_f32_e32 v3, v30, v30
	v_fmac_f32_e32 v31, v32, v32
	v_mul_f32_e32 v35, v51, v51
	v_mul_f32_e32 v36, v53, v53
	v_fmac_f32_e32 v33, v90, v90
	v_fmac_f32_e32 v34, v92, v92
	v_add_f32_e32 v3, v3, v31
	v_fmac_f32_e32 v35, v50, v50
	v_fmac_f32_e32 v36, v52, v52
	v_add_f32_e32 v13, v33, v34
	v_add_f32_e32 v3, v3, v10
	v_add_f32_e32 v10, v15, v11
	v_add_f32_e32 v16, v35, v36
	v_add_f32_e32 v3, v3, v12
	v_add_f32_e32 v10, v10, v13
	v_add_f32_e32 v3, v3, v14
	v_add_f32_e32 v12, v10, v16
	ds_bpermute_b32 v5, v146, v4
	ds_bpermute_b32 v14, v146, v3
	ds_bpermute_b32 v15, v146, v12
	ds_bpermute_b32 v10, v147, v2
	s_waitcnt lgkmcnt(3)
	v_add_f32_e32 v11, v4, v5
	s_waitcnt lgkmcnt(2)
	v_add_f32_e32 v3, v3, v14
	s_waitcnt lgkmcnt(1)
	v_add_f32_e32 v5, v12, v15
	ds_bpermute_b32 v13, v147, v11
	ds_bpermute_b32 v4, v147, v3
	ds_bpermute_b32 v12, v147, v5
	s_waitcnt vmcnt(0)
	v_pk_mul_f32 v[14:15], v[52:53], v[56:57]
	v_pk_mul_f32 v[16:17], v[50:51], v[54:55]
	s_nop 0
	v_cvt_pk_bf16_f32 v16, v16, v17
	v_cvt_pk_bf16_f32 v17, v14, v15
	global_store_dwordx2 v[70:71], v[16:17], off offset:32
	s_and_saveexec_b64 s[36:37], s[0:1]
	s_cbranch_execz .LBB0_1108
	s_waitcnt lgkmcnt(3)
	v_add_f32_e32 v10, v2, v10
	v_add_f32_e32 v6, v6, v8
	s_waitcnt lgkmcnt(1)
	v_add_f32_e32 v4, v3, v4
	v_lshl_add_u64 v[2:3], v[220:221], 2, s[6:7]
	v_add_f32_e32 v11, v11, v13
	v_add_f32_e32 v13, v67, v69
	v_add_f32_e32 v9, v9, v68
	v_add_f32_e32 v7, v7, v66
	s_waitcnt lgkmcnt(0)
	v_add_f32_e32 v5, v5, v12
	global_atomic_add_f32 v[2:3], v6, off
	global_atomic_add_f32 v[2:3], v7, off offset:64
	global_atomic_add_f32 v[2:3], v9, off offset:128
	global_atomic_add_f32 v[2:3], v13, off offset:192
	global_atomic_add_f32 v[2:3], v10, off offset:512
	global_atomic_add_f32 v[2:3], v11, off offset:576
	global_atomic_add_f32 v[2:3], v4, off offset:640
	global_atomic_add_f32 v[2:3], v5, off offset:704
